# passC pooling: the first four conditional U-row loads of each half-chunk issued together into separate registers, one wait, then the LDS writes (was load-wait-write per row group); plus carry-fold de-
# speedup vs baseline: 1.0062x; 1.0059x over previous
.LBB0_487:
	s_ashr_i32 s0, s18, 1
	s_lshl_b32 s1, s0, 6
	s_and_b32 s4, s22, 0xffffff00
	s_cmp_gt_i32 s0, 63
	s_cselect_b32 s25, 64, 0x100
	s_cselect_b32 s26, s1, s4
	s_and_b32 s0, s22, 32
	s_or_b32 s24, s1, s0
	s_add_i32 s27, s25, s26
	s_mov_b64 s[0:1], -1
	s_mov_b64 s[4:5], 0
	s_cmp_lt_i32 s20, 1
	s_mov_b64 s[6:7], 0
	s_cbranch_scc1 .LBB0_535
	s_cmp_gt_i32 s20, 1
	s_cbranch_scc0 .LBB0_504
	s_cmp_eq_u32 s20, 2
	s_mov_b64 s[6:7], -1
	s_cbranch_scc0 .LBB0_503
	s_add_i32 s13, s24, -4
	v_add_u32_e32 v1, s13, v99
	v_cmp_le_i32_e32 vcc, s26, v1
	v_cmp_gt_i32_e64 s[0:1], s27, v1
	s_and_b64 s[6:7], vcc, s[0:1]
	v_mov_b32_e32 v0, 0
	v_mov_b32_e32 v2, 0
	v_mov_b32_e32 v3, 0
	v_mov_b32_e32 v4, 0
	v_mov_b32_e32 v5, 0
	v_mov_b32_e32 v226, 0
	v_mov_b32_e32 v227, 0
	v_mov_b32_e32 v228, 0
	v_mov_b32_e32 v229, 0
	s_and_saveexec_b64 s[0:1], s[6:7]
	s_cbranch_execz .LBB0_492
	v_mad_i64_i32 v[226:227], s[6:7], v1, s53, v[6:7]
	global_load_dwordx4 v[226:229], v[226:227], off
.LBB0_492:
	s_or_b64 exec, exec, s[0:1]
	v_add_u32_e32 v4, s13, v118
	v_cmp_le_i32_e32 vcc, s26, v4
	v_cmp_gt_i32_e64 s[0:1], s27, v4
	s_and_b64 s[6:7], vcc, s[0:1]
	v_mov_b32_e32 v1, 0
	v_mov_b32_e32 v2, 0
	v_mov_b32_e32 v3, 0
	v_mov_b32_e32 v230, 0
	v_mov_b32_e32 v231, 0
	v_mov_b32_e32 v232, 0
	v_mov_b32_e32 v233, 0
	s_and_saveexec_b64 s[0:1], s[6:7]
	s_cbranch_execz .LBB0_494
	v_mad_i64_i32 v[230:231], s[6:7], v4, s53, v[6:7]
	global_load_dwordx4 v[230:233], v[230:231], off
.LBB0_494:
	s_or_b64 exec, exec, s[0:1]
	v_add_u32_e32 v1, s13, v119
	v_cmp_le_i32_e32 vcc, s26, v1
	v_cmp_gt_i32_e64 s[0:1], s27, v1
	s_and_b64 s[6:7], vcc, s[0:1]
	v_mov_b32_e32 v0, 0
	v_mov_b32_e32 v2, 0
	v_mov_b32_e32 v3, 0
	v_mov_b32_e32 v4, 0
	v_mov_b32_e32 v5, 0
	v_mov_b32_e32 v234, 0
	v_mov_b32_e32 v235, 0
	v_mov_b32_e32 v236, 0
	v_mov_b32_e32 v237, 0
	s_and_saveexec_b64 s[0:1], s[6:7]
	s_cbranch_execz .LBB0_496
	v_mad_i64_i32 v[234:235], s[6:7], v1, s53, v[6:7]
	global_load_dwordx4 v[234:237], v[234:235], off
.LBB0_496:
	s_or_b64 exec, exec, s[0:1]
	v_add_u32_e32 v4, s13, v120
	v_cmp_le_i32_e32 vcc, s26, v4
	v_cmp_gt_i32_e64 s[0:1], s27, v4
	s_and_b64 s[6:7], vcc, s[0:1]
	v_mov_b32_e32 v1, 0
	v_mov_b32_e32 v2, 0
	v_mov_b32_e32 v3, 0
	v_mov_b32_e32 v238, 0
	v_mov_b32_e32 v239, 0
	v_mov_b32_e32 v240, 0
	v_mov_b32_e32 v241, 0
	s_and_saveexec_b64 s[0:1], s[6:7]
	s_cbranch_execz .LBB0_498
	v_mad_i64_i32 v[238:239], s[6:7], v4, s53, v[6:7]
	global_load_dwordx4 v[238:241], v[238:239], off
.LBB0_498:
	s_or_b64 exec, exec, s[0:1]
	s_waitcnt vmcnt(0)
	v_add_u32_e32 v18, v10, v11
	ds_write_b128 v18, v[226:229]
	v_add_u32_e32 v19, v10, v12
	ds_write_b128 v19, v[230:233]
	v_add_u32_e32 v20, v10, v13
	ds_write_b128 v20, v[234:237]
	v_add_u32_e32 v4, v10, v14
	ds_write_b128 v4, v[238:241]
	s_and_saveexec_b64 s[6:7], s[40:41]
	s_cbranch_execz .LBB0_502
	v_add_u32_e32 v5, s13, v121
	v_cmp_le_i32_e32 vcc, s26, v5
	v_cmp_gt_i32_e64 s[0:1], s27, v5
	s_and_b64 s[16:17], vcc, s[0:1]
	v_mov_b32_e32 v0, 0
	v_mov_b32_e32 v1, 0
	v_mov_b32_e32 v2, 0
	v_mov_b32_e32 v3, 0
	s_and_saveexec_b64 s[0:1], s[16:17]
	s_cbranch_execz .LBB0_501
	v_mad_i64_i32 v[0:1], s[16:17], v5, s53, v[6:7]
	global_load_dwordx4 v[0:3], v[0:1], off

.LBB0_504:
	s_and_b64 vcc, exec, s[0:1]
	s_cbranch_vccz .LBB0_518
	s_add_i32 s13, s24, -2
	v_add_u32_e32 v1, s13, v99
	v_cmp_le_i32_e32 vcc, s26, v1
	v_cmp_gt_i32_e64 s[0:1], s27, v1
	s_and_b64 s[16:17], vcc, s[0:1]
	v_mov_b32_e32 v0, 0
	v_mov_b32_e32 v2, 0
	v_mov_b32_e32 v3, 0
	v_mov_b32_e32 v4, 0
	v_mov_b32_e32 v5, 0
	v_mov_b32_e32 v226, 0
	v_mov_b32_e32 v227, 0
	v_mov_b32_e32 v228, 0
	v_mov_b32_e32 v229, 0
	s_and_saveexec_b64 s[0:1], s[16:17]
	s_cbranch_execz .LBB0_507
	v_mad_i64_i32 v[226:227], s[16:17], v1, s53, v[6:7]
	global_load_dwordx4 v[226:229], v[226:227], off
.LBB0_507:
	s_or_b64 exec, exec, s[0:1]
	v_add_u32_e32 v4, s13, v118
	v_cmp_le_i32_e32 vcc, s26, v4
	v_cmp_gt_i32_e64 s[0:1], s27, v4
	s_and_b64 s[16:17], vcc, s[0:1]
	v_mov_b32_e32 v1, 0
	v_mov_b32_e32 v2, 0
	v_mov_b32_e32 v3, 0
	v_mov_b32_e32 v230, 0
	v_mov_b32_e32 v231, 0
	v_mov_b32_e32 v232, 0
	v_mov_b32_e32 v233, 0
	s_and_saveexec_b64 s[0:1], s[16:17]
	s_cbranch_execz .LBB0_509
	v_mad_i64_i32 v[230:231], s[16:17], v4, s53, v[6:7]
	global_load_dwordx4 v[230:233], v[230:231], off
.LBB0_509:
	s_or_b64 exec, exec, s[0:1]
	v_add_u32_e32 v1, s13, v119
	v_cmp_le_i32_e32 vcc, s26, v1
	v_cmp_gt_i32_e64 s[0:1], s27, v1
	s_and_b64 s[16:17], vcc, s[0:1]
	v_mov_b32_e32 v0, 0
	v_mov_b32_e32 v2, 0
	v_mov_b32_e32 v3, 0
	v_mov_b32_e32 v4, 0
	v_mov_b32_e32 v5, 0
	v_mov_b32_e32 v234, 0
	v_mov_b32_e32 v235, 0
	v_mov_b32_e32 v236, 0
	v_mov_b32_e32 v237, 0
	s_and_saveexec_b64 s[0:1], s[16:17]
	s_cbranch_execz .LBB0_511
	v_mad_i64_i32 v[234:235], s[16:17], v1, s53, v[6:7]
	global_load_dwordx4 v[234:237], v[234:235], off
.LBB0_511:
	s_or_b64 exec, exec, s[0:1]
	v_add_u32_e32 v4, s13, v120
	v_cmp_le_i32_e32 vcc, s26, v4
	v_cmp_gt_i32_e64 s[0:1], s27, v4
	s_and_b64 s[16:17], vcc, s[0:1]
	v_mov_b32_e32 v1, 0
	v_mov_b32_e32 v2, 0
	v_mov_b32_e32 v3, 0
	v_mov_b32_e32 v238, 0
	v_mov_b32_e32 v239, 0
	v_mov_b32_e32 v240, 0
	v_mov_b32_e32 v241, 0
	s_and_saveexec_b64 s[0:1], s[16:17]
	s_cbranch_execz .LBB0_513
	v_mad_i64_i32 v[238:239], s[16:17], v4, s53, v[6:7]
	global_load_dwordx4 v[238:241], v[238:239], off
.LBB0_513:
	s_or_b64 exec, exec, s[0:1]
	s_waitcnt vmcnt(0)
	v_add_u32_e32 v18, v10, v11
	ds_write_b128 v18, v[226:229]
	v_add_u32_e32 v19, v10, v12
	ds_write_b128 v19, v[230:233]
	v_add_u32_e32 v20, v10, v13
	ds_write_b128 v20, v[234:237]
	v_add_u32_e32 v4, v10, v14
	ds_write_b128 v4, v[238:241]
	s_and_saveexec_b64 s[16:17], s[42:43]
	s_cbranch_execz .LBB0_517
	v_add_u32_e32 v5, s13, v121
	v_cmp_le_i32_e32 vcc, s26, v5
	v_cmp_gt_i32_e64 s[0:1], s27, v5
	s_and_b64 s[28:29], vcc, s[0:1]
	v_mov_b32_e32 v0, 0
	v_mov_b32_e32 v1, 0
	v_mov_b32_e32 v2, 0
	v_mov_b32_e32 v3, 0
	s_and_saveexec_b64 s[0:1], s[28:29]
	s_cbranch_execz .LBB0_516
	v_mad_i64_i32 v[0:1], s[28:29], v5, s53, v[6:7]
	global_load_dwordx4 v[0:3], v[0:1], off

.LBB0_520:
	s_add_i32 s6, s24, -8
	v_or_b32_e32 v1, s6, v99
	v_cmp_le_i32_e32 vcc, s26, v1
	v_cmp_gt_i32_e64 s[0:1], s27, v1
	s_and_b64 s[4:5], vcc, s[0:1]
	v_mov_b32_e32 v0, 0
	v_mov_b32_e32 v2, 0
	v_mov_b32_e32 v3, 0
	v_mov_b32_e32 v4, 0
	v_mov_b32_e32 v5, 0
	v_mov_b32_e32 v226, 0
	v_mov_b32_e32 v227, 0
	v_mov_b32_e32 v228, 0
	v_mov_b32_e32 v229, 0
	s_and_saveexec_b64 s[0:1], s[4:5]
	s_cbranch_execz .LBB0_522
	v_mad_i64_i32 v[226:227], s[4:5], v1, s53, v[6:7]
	global_load_dwordx4 v[226:229], v[226:227], off
.LBB0_522:
	s_or_b64 exec, exec, s[0:1]
	v_add_u32_e32 v4, s6, v118
	v_cmp_le_i32_e32 vcc, s26, v4
	v_cmp_gt_i32_e64 s[0:1], s27, v4
	s_and_b64 s[4:5], vcc, s[0:1]
	v_mov_b32_e32 v1, 0
	v_mov_b32_e32 v2, 0
	v_mov_b32_e32 v3, 0
	v_mov_b32_e32 v230, 0
	v_mov_b32_e32 v231, 0
	v_mov_b32_e32 v232, 0
	v_mov_b32_e32 v233, 0
	s_and_saveexec_b64 s[0:1], s[4:5]
	s_cbranch_execz .LBB0_524
	v_mad_i64_i32 v[230:231], s[4:5], v4, s53, v[6:7]
	global_load_dwordx4 v[230:233], v[230:231], off
.LBB0_524:
	s_or_b64 exec, exec, s[0:1]
	v_add_u32_e32 v1, s6, v119
	v_cmp_le_i32_e32 vcc, s26, v1
	v_cmp_gt_i32_e64 s[0:1], s27, v1
	s_and_b64 s[4:5], vcc, s[0:1]
	v_mov_b32_e32 v0, 0
	v_mov_b32_e32 v2, 0
	v_mov_b32_e32 v3, 0
	v_mov_b32_e32 v4, 0
	v_mov_b32_e32 v5, 0
	v_mov_b32_e32 v234, 0
	v_mov_b32_e32 v235, 0
	v_mov_b32_e32 v236, 0
	v_mov_b32_e32 v237, 0
	s_and_saveexec_b64 s[0:1], s[4:5]
	s_cbranch_execz .LBB0_526
	v_mad_i64_i32 v[234:235], s[4:5], v1, s53, v[6:7]
	global_load_dwordx4 v[234:237], v[234:235], off
.LBB0_526:
	s_or_b64 exec, exec, s[0:1]
	v_add_u32_e32 v4, s6, v120
	v_cmp_le_i32_e32 vcc, s26, v4
	v_cmp_gt_i32_e64 s[0:1], s27, v4
	s_and_b64 s[4:5], vcc, s[0:1]
	v_mov_b32_e32 v1, 0
	v_mov_b32_e32 v2, 0
	v_mov_b32_e32 v3, 0
	v_mov_b32_e32 v238, 0
	v_mov_b32_e32 v239, 0
	v_mov_b32_e32 v240, 0
	v_mov_b32_e32 v241, 0
	s_and_saveexec_b64 s[0:1], s[4:5]
	s_cbranch_execz .LBB0_528
	v_mad_i64_i32 v[238:239], s[4:5], v4, s53, v[6:7]
	global_load_dwordx4 v[238:241], v[238:239], off
.LBB0_528:
	s_or_b64 exec, exec, s[0:1]
	v_add_u32_e32 v5, s6, v121
	v_cmp_le_i32_e32 vcc, s26, v5
	v_cmp_gt_i32_e64 s[0:1], s27, v5
	s_waitcnt vmcnt(0)
	v_add_u32_e32 v18, v10, v11
	ds_write_b128 v18, v[226:229]
	v_add_u32_e32 v19, v10, v12
	ds_write_b128 v19, v[230:233]
	v_add_u32_e32 v20, v10, v13
	ds_write_b128 v20, v[234:237]
	v_add_u32_e32 v4, v10, v14
	ds_write_b128 v4, v[238:241]
	s_and_b64 s[4:5], vcc, s[0:1]
	v_mov_b32_e32 v0, 0
	v_mov_b32_e32 v1, 0
	v_mov_b32_e32 v2, 0
	v_mov_b32_e32 v3, 0
	s_and_saveexec_b64 s[0:1], s[4:5]
	s_cbranch_execz .LBB0_530
	v_mad_i64_i32 v[0:1], s[4:5], v5, s53, v[6:7]
	global_load_dwordx4 v[0:3], v[0:1], off

.LBB0_537:
	s_and_b64 vcc, exec, s[4:5]
	s_cbranch_vccz .LBB0_486
	s_add_i32 s4, s24, -1
	v_add_u32_e32 v1, s4, v99
	v_cmp_le_i32_e32 vcc, s26, v1
	v_cmp_gt_i32_e64 s[0:1], s27, v1
	s_and_b64 s[6:7], vcc, s[0:1]
	v_mov_b32_e32 v0, 0
	v_mov_b32_e32 v2, 0
	v_mov_b32_e32 v3, 0
	v_mov_b32_e32 v4, 0
	v_mov_b32_e32 v5, 0
	v_mov_b32_e32 v226, 0
	v_mov_b32_e32 v227, 0
	v_mov_b32_e32 v228, 0
	v_mov_b32_e32 v229, 0
	s_and_saveexec_b64 s[0:1], s[6:7]
	s_cbranch_execz .LBB0_540
	v_mad_i64_i32 v[226:227], s[6:7], v1, s53, v[6:7]
	global_load_dwordx4 v[226:229], v[226:227], off
.LBB0_540:
	s_or_b64 exec, exec, s[0:1]
	v_add_u32_e32 v4, s4, v118
	v_cmp_le_i32_e32 vcc, s26, v4
	v_cmp_gt_i32_e64 s[0:1], s27, v4
	s_and_b64 s[6:7], vcc, s[0:1]
	v_mov_b32_e32 v1, 0
	v_mov_b32_e32 v2, 0
	v_mov_b32_e32 v3, 0
	v_mov_b32_e32 v230, 0
	v_mov_b32_e32 v231, 0
	v_mov_b32_e32 v232, 0
	v_mov_b32_e32 v233, 0
	s_and_saveexec_b64 s[0:1], s[6:7]
	s_cbranch_execz .LBB0_542
	v_mad_i64_i32 v[230:231], s[6:7], v4, s53, v[6:7]
	global_load_dwordx4 v[230:233], v[230:231], off
.LBB0_542:
	s_or_b64 exec, exec, s[0:1]
	v_add_u32_e32 v1, s4, v119
	v_cmp_le_i32_e32 vcc, s26, v1
	v_cmp_gt_i32_e64 s[0:1], s27, v1
	s_and_b64 s[6:7], vcc, s[0:1]
	v_mov_b32_e32 v0, 0
	v_mov_b32_e32 v2, 0
	v_mov_b32_e32 v3, 0
	v_mov_b32_e32 v4, 0
	v_mov_b32_e32 v5, 0
	v_mov_b32_e32 v234, 0
	v_mov_b32_e32 v235, 0
	v_mov_b32_e32 v236, 0
	v_mov_b32_e32 v237, 0
	s_and_saveexec_b64 s[0:1], s[6:7]
	s_cbranch_execz .LBB0_544
	v_mad_i64_i32 v[234:235], s[6:7], v1, s53, v[6:7]
	global_load_dwordx4 v[234:237], v[234:235], off
.LBB0_544:
	s_or_b64 exec, exec, s[0:1]
	v_add_u32_e32 v4, s4, v120
	v_cmp_le_i32_e32 vcc, s26, v4
	v_cmp_gt_i32_e64 s[0:1], s27, v4
	s_and_b64 s[4:5], vcc, s[0:1]
	v_mov_b32_e32 v1, 0
	v_mov_b32_e32 v2, 0
	v_mov_b32_e32 v3, 0
	v_mov_b32_e32 v238, 0
	v_mov_b32_e32 v239, 0
	v_mov_b32_e32 v240, 0
	v_mov_b32_e32 v241, 0
	s_and_saveexec_b64 s[0:1], s[4:5]
	s_cbranch_execz .LBB0_546
	v_mad_i64_i32 v[238:239], s[4:5], v4, s53, v[6:7]
	global_load_dwordx4 v[238:241], v[238:239], off
.LBB0_546:
	s_or_b64 exec, exec, s[0:1]
	s_waitcnt vmcnt(0)
	v_add_u32_e32 v18, v10, v11
	ds_write_b128 v18, v[226:229]
	v_add_u32_e32 v19, v10, v12
	ds_write_b128 v19, v[230:233]
	v_add_u32_e32 v20, v10, v13
	ds_write_b128 v20, v[234:237]
	v_add_u32_e32 v4, v10, v14
	ds_write_b128 v4, v[238:241]
	s_and_saveexec_b64 s[0:1], s[44:45]
	s_cbranch_execz .LBB0_485
	s_or_b32 s4, s24, 31
	s_cmp_ge_i32 s4, s26
	s_cselect_b64 s[6:7], -1, 0
	s_cmp_lt_i32 s4, s27
	s_cselect_b64 s[16:17], -1, 0
	s_and_b64 s[6:7], s[6:7], s[16:17]
	v_mov_b32_e32 v0, 0
	s_andn2_b64 vcc, exec, s[6:7]
	v_mov_b32_e32 v1, 0
	v_mov_b32_e32 v2, 0
	v_mov_b32_e32 v3, 0
	s_cbranch_vccnz .LBB0_484
	v_mad_i64_i32 v[0:1], s[4:5], s4, v208, v[6:7]
	global_load_dwordx4 v[0:3], v[0:1], off
	s_branch .LBB0_484
